# nt (streaming) row stores also in phase 1 (h0) and phase 6 (readout) in addition to the LN phases
# baseline (speedup 1.0000x reference)
.LBB0_117:
	v_and_b32_e32 v2, 8, v5
	v_mul_u32_u24_e32 v2, 0x1800, v2
	v_and_or_b32 v2, v6, s6, v2
	v_lshlrev_b32_e32 v2, 2, v2
	global_load_dword v7, v2, s[0:1]
	v_lshl_add_u64 v[8:9], s[0:1], 0, v[2:3]
	v_add_co_u32_e32 v10, vcc, 0x6000, v8
	v_add_u32_e32 v12, 0x12000, v2
	s_nop 0
	v_addc_co_u32_e32 v11, vcc, 0, v9, vcc
	v_add_co_u32_e32 v8, vcc, 0xc000, v8
	v_add_u32_e32 v13, 0x18000, v2
	v_add_u32_e32 v14, 0x1e000, v2
	v_add_u32_e32 v15, 0x24000, v2
	v_add_u32_e32 v2, 0x2a000, v2
	v_addc_co_u32_e32 v9, vcc, 0, v9, vcc
	global_load_dword v10, v[10:11], off
	s_nop 0
	global_load_dword v8, v[8:9], off
	s_nop 0
	global_load_dword v9, v12, s[0:1]
	global_load_dword v11, v13, s[0:1]
	s_nop 0
	global_load_dword v12, v14, s[0:1]
	global_load_dword v13, v15, s[0:1]
	s_nop 0
	global_load_dword v2, v2, s[0:1]
	v_add_u32_e32 v14, 0x200, v6
	v_cmp_lt_u32_e32 vcc, s7, v6
	v_add_u32_e32 v5, 2, v5
	s_or_b64 s[4:5], vcc, s[4:5]
	v_mov_b32_e32 v6, v14
	s_waitcnt vmcnt(7)
	v_add_f32_e32 v7, 0, v7
	s_waitcnt vmcnt(6)
	v_add_f32_e32 v7, v7, v10
	s_waitcnt vmcnt(5)
	v_add_f32_e32 v7, v7, v8
	s_waitcnt vmcnt(4)
	v_add_f32_e32 v7, v7, v9
	s_waitcnt vmcnt(3)
	v_add_f32_e32 v7, v7, v11
	s_waitcnt vmcnt(2)
	v_add_f32_e32 v7, v7, v12
	s_waitcnt vmcnt(1)
	v_add_f32_e32 v7, v7, v13
	s_waitcnt vmcnt(0)
	v_add_f32_e32 v2, v7, v2
	ds_write_b32 v4, v2
	v_add_u32_e32 v4, 0x800, v4
	s_andn2_b64 exec, exec, s[4:5]
	s_cbranch_execnz .LBB0_117
	s_or_b64 exec, exec, s[4:5]
	v_lshrrev_b32_e32 v2, 6, v188
	v_lshl_add_u32 v6, s33, 3, v2
	s_movk_i32 s10, 0x4100
	v_cmp_gt_i32_e32 vcc, s10, v6
	s_waitcnt lgkmcnt(0)
	s_barrier
	s_and_saveexec_b64 s[0:1], vcc
	s_cbranch_execz .LBB0_131
	v_and_b32_e32 v1, 63, v188
	v_lshlrev_b32_e32 v2, 4, v1
	v_lshlrev_b32_e32 v3, 3, v1
	v_readfirstlane_b32 s8, v188
	s_lshr_b32 s8, s8, 6
	s_lshl_b32 s9, s33, 3
	s_add_i32 s9, s9, s8
	s_lshl_b32 s10, s9, 12
	s_add_u32 s4, s52, s10
	s_addc_u32 s5, s53, 0
	s_lshl_b32 s11, s9, 11
	s_add_u32 s6, s54, s11
	s_addc_u32 s7, s55, 0
	global_load_dwordx4 v[40:43], v2, s[4:5]
	global_load_dwordx4 v[44:47], v2, s[4:5] offset:1024
	global_load_dwordx4 v[48:51], v2, s[4:5] offset:2048
	global_load_dwordx4 v[52:55], v2, s[4:5] offset:3072
	s_add_u32 s4, s4, 0x800000
	s_addc_u32 s5, s5, 0
	global_load_dwordx4 v[56:59], v2, s[4:5]
	global_load_dwordx4 v[60:63], v2, s[4:5] offset:1024
	global_load_dwordx4 v[64:67], v2, s[4:5] offset:2048
	global_load_dwordx4 v[68:71], v2, s[4:5] offset:3072
	s_add_u32 s4, s4, 0x800000
	s_addc_u32 s5, s5, 0
	ds_read_b128 v[8:11], v2 offset:0
	ds_read_b128 v[12:15], v2 offset:1024
	ds_read_b128 v[16:19], v2 offset:2048
	ds_read_b128 v[20:23], v2 offset:3072
	ds_read_b128 v[24:27], v2 offset:4096
	ds_read_b128 v[28:31], v2 offset:5120
	ds_read_b128 v[32:35], v2 offset:6144
	ds_read_b128 v[36:39], v2 offset:7168
	s_waitcnt lgkmcnt(0)
	v_pk_add_f32 v[24:25], v[24:25], 1.0 op_sel_hi:[1,0]
	v_pk_add_f32 v[26:27], v[26:27], 1.0 op_sel_hi:[1,0]
	v_pk_add_f32 v[28:29], v[28:29], 1.0 op_sel_hi:[1,0]
	v_pk_add_f32 v[30:31], v[30:31], 1.0 op_sel_hi:[1,0]
	v_pk_add_f32 v[32:33], v[32:33], 1.0 op_sel_hi:[1,0]
	v_pk_add_f32 v[34:35], v[34:35], 1.0 op_sel_hi:[1,0]
	v_pk_add_f32 v[36:37], v[36:37], 1.0 op_sel_hi:[1,0]
	v_pk_add_f32 v[38:39], v[38:39], 1.0 op_sel_hi:[1,0]
	s_waitcnt vmcnt(4)
	v_pk_fma_f32 v[40:41], v[40:41], v[24:25], v[8:9]
	v_pk_fma_f32 v[42:43], v[42:43], v[26:27], v[10:11]
	v_pk_fma_f32 v[44:45], v[44:45], v[28:29], v[12:13]
	v_pk_fma_f32 v[46:47], v[46:47], v[30:31], v[14:15]
	v_pk_fma_f32 v[48:49], v[48:49], v[32:33], v[16:17]
	v_pk_fma_f32 v[50:51], v[50:51], v[34:35], v[18:19]
	v_pk_fma_f32 v[52:53], v[52:53], v[36:37], v[20:21]
	v_pk_fma_f32 v[54:55], v[54:55], v[38:39], v[22:23]
	v_cvt_pk_bf16_f32 v72, v40, v41
	v_cvt_pk_bf16_f32 v73, v42, v43
	v_cvt_pk_bf16_f32 v74, v44, v45
	v_cvt_pk_bf16_f32 v75, v46, v47
	v_cvt_pk_bf16_f32 v76, v48, v49
	v_cvt_pk_bf16_f32 v77, v50, v51
	v_cvt_pk_bf16_f32 v78, v52, v53
	v_cvt_pk_bf16_f32 v79, v54, v55
	global_store_dwordx2 v3, v[72:73], s[6:7] nt
	global_store_dwordx2 v3, v[74:75], s[6:7] offset:512 nt
	global_store_dwordx2 v3, v[76:77], s[6:7] offset:1024 nt
	global_store_dwordx2 v3, v[78:79], s[6:7] offset:1536 nt
	s_add_u32 s6, s6, 0x400000
	s_addc_u32 s7, s7, 0
	global_load_dwordx4 v[40:43], v2, s[4:5]
	global_load_dwordx4 v[44:47], v2, s[4:5] offset:1024
	global_load_dwordx4 v[48:51], v2, s[4:5] offset:2048
	global_load_dwordx4 v[52:55], v2, s[4:5] offset:3072
	s_add_u32 s4, s4, 0x800000
	s_addc_u32 s5, s5, 0
	s_waitcnt vmcnt(8)
	v_pk_fma_f32 v[56:57], v[56:57], v[24:25], v[8:9]
	v_pk_fma_f32 v[58:59], v[58:59], v[26:27], v[10:11]
	v_pk_fma_f32 v[60:61], v[60:61], v[28:29], v[12:13]
	v_pk_fma_f32 v[62:63], v[62:63], v[30:31], v[14:15]
	v_pk_fma_f32 v[64:65], v[64:65], v[32:33], v[16:17]
	v_pk_fma_f32 v[66:67], v[66:67], v[34:35], v[18:19]
	v_pk_fma_f32 v[68:69], v[68:69], v[36:37], v[20:21]
	v_pk_fma_f32 v[70:71], v[70:71], v[38:39], v[22:23]
	v_cvt_pk_bf16_f32 v80, v56, v57
	v_cvt_pk_bf16_f32 v81, v58, v59
	v_cvt_pk_bf16_f32 v82, v60, v61
	v_cvt_pk_bf16_f32 v83, v62, v63
	v_cvt_pk_bf16_f32 v84, v64, v65
	v_cvt_pk_bf16_f32 v85, v66, v67
	v_cvt_pk_bf16_f32 v86, v68, v69
	v_cvt_pk_bf16_f32 v87, v70, v71
	global_store_dwordx2 v3, v[80:81], s[6:7] nt
	global_store_dwordx2 v3, v[82:83], s[6:7] offset:512 nt
	global_store_dwordx2 v3, v[84:85], s[6:7] offset:1024 nt
	global_store_dwordx2 v3, v[86:87], s[6:7] offset:1536 nt
	s_add_u32 s6, s6, 0x400000
	s_addc_u32 s7, s7, 0
	global_load_dwordx4 v[56:59], v2, s[4:5]
	global_load_dwordx4 v[60:63], v2, s[4:5] offset:1024
	global_load_dwordx4 v[64:67], v2, s[4:5] offset:2048
	global_load_dwordx4 v[68:71], v2, s[4:5] offset:3072
	s_add_u32 s4, s4, 0x800000
	s_addc_u32 s5, s5, 0
	s_waitcnt vmcnt(8)
	v_pk_fma_f32 v[40:41], v[40:41], v[24:25], v[8:9]
	v_pk_fma_f32 v[42:43], v[42:43], v[26:27], v[10:11]
	v_pk_fma_f32 v[44:45], v[44:45], v[28:29], v[12:13]
	v_pk_fma_f32 v[46:47], v[46:47], v[30:31], v[14:15]
	v_pk_fma_f32 v[48:49], v[48:49], v[32:33], v[16:17]
	v_pk_fma_f32 v[50:51], v[50:51], v[34:35], v[18:19]
	v_pk_fma_f32 v[52:53], v[52:53], v[36:37], v[20:21]
	v_pk_fma_f32 v[54:55], v[54:55], v[38:39], v[22:23]
	v_cvt_pk_bf16_f32 v72, v40, v41
	v_cvt_pk_bf16_f32 v73, v42, v43
	v_cvt_pk_bf16_f32 v74, v44, v45
	v_cvt_pk_bf16_f32 v75, v46, v47
	v_cvt_pk_bf16_f32 v76, v48, v49
	v_cvt_pk_bf16_f32 v77, v50, v51
	v_cvt_pk_bf16_f32 v78, v52, v53
	v_cvt_pk_bf16_f32 v79, v54, v55
	global_store_dwordx2 v3, v[72:73], s[6:7] nt
	global_store_dwordx2 v3, v[74:75], s[6:7] offset:512 nt
	global_store_dwordx2 v3, v[76:77], s[6:7] offset:1024 nt
	global_store_dwordx2 v3, v[78:79], s[6:7] offset:1536 nt
	s_add_u32 s6, s6, 0x400000
	s_addc_u32 s7, s7, 0
	global_load_dwordx4 v[40:43], v2, s[4:5]
	global_load_dwordx4 v[44:47], v2, s[4:5] offset:1024
	global_load_dwordx4 v[48:51], v2, s[4:5] offset:2048
	global_load_dwordx4 v[52:55], v2, s[4:5] offset:3072
	s_add_u32 s4, s4, 0x800000
	s_addc_u32 s5, s5, 0
	s_waitcnt vmcnt(8)
	v_pk_fma_f32 v[56:57], v[56:57], v[24:25], v[8:9]
	v_pk_fma_f32 v[58:59], v[58:59], v[26:27], v[10:11]
	v_pk_fma_f32 v[60:61], v[60:61], v[28:29], v[12:13]
	v_pk_fma_f32 v[62:63], v[62:63], v[30:31], v[14:15]
	v_pk_fma_f32 v[64:65], v[64:65], v[32:33], v[16:17]
	v_pk_fma_f32 v[66:67], v[66:67], v[34:35], v[18:19]
	v_pk_fma_f32 v[68:69], v[68:69], v[36:37], v[20:21]
	v_pk_fma_f32 v[70:71], v[70:71], v[38:39], v[22:23]
	v_cvt_pk_bf16_f32 v80, v56, v57
	v_cvt_pk_bf16_f32 v81, v58, v59
	v_cvt_pk_bf16_f32 v82, v60, v61
	v_cvt_pk_bf16_f32 v83, v62, v63
	v_cvt_pk_bf16_f32 v84, v64, v65
	v_cvt_pk_bf16_f32 v85, v66, v67
	v_cvt_pk_bf16_f32 v86, v68, v69
	v_cvt_pk_bf16_f32 v87, v70, v71
	global_store_dwordx2 v3, v[80:81], s[6:7] nt
	global_store_dwordx2 v3, v[82:83], s[6:7] offset:512 nt
	global_store_dwordx2 v3, v[84:85], s[6:7] offset:1024 nt
	global_store_dwordx2 v3, v[86:87], s[6:7] offset:1536 nt
	s_add_u32 s6, s6, 0x400000
	s_addc_u32 s7, s7, 0
	global_load_dwordx4 v[56:59], v2, s[4:5]
	global_load_dwordx4 v[60:63], v2, s[4:5] offset:1024
	global_load_dwordx4 v[64:67], v2, s[4:5] offset:2048
	global_load_dwordx4 v[68:71], v2, s[4:5] offset:3072
	s_add_u32 s4, s4, 0x800000
	s_addc_u32 s5, s5, 0
	s_waitcnt vmcnt(8)
	v_pk_fma_f32 v[40:41], v[40:41], v[24:25], v[8:9]
	v_pk_fma_f32 v[42:43], v[42:43], v[26:27], v[10:11]
	v_pk_fma_f32 v[44:45], v[44:45], v[28:29], v[12:13]
	v_pk_fma_f32 v[46:47], v[46:47], v[30:31], v[14:15]
	v_pk_fma_f32 v[48:49], v[48:49], v[32:33], v[16:17]
	v_pk_fma_f32 v[50:51], v[50:51], v[34:35], v[18:19]
	v_pk_fma_f32 v[52:53], v[52:53], v[36:37], v[20:21]
	v_pk_fma_f32 v[54:55], v[54:55], v[38:39], v[22:23]
	v_cvt_pk_bf16_f32 v72, v40, v41
	v_cvt_pk_bf16_f32 v73, v42, v43
	v_cvt_pk_bf16_f32 v74, v44, v45
	v_cvt_pk_bf16_f32 v75, v46, v47
	v_cvt_pk_bf16_f32 v76, v48, v49
	v_cvt_pk_bf16_f32 v77, v50, v51
	v_cvt_pk_bf16_f32 v78, v52, v53
	v_cvt_pk_bf16_f32 v79, v54, v55
	global_store_dwordx2 v3, v[72:73], s[6:7] nt
	global_store_dwordx2 v3, v[74:75], s[6:7] offset:512 nt
	global_store_dwordx2 v3, v[76:77], s[6:7] offset:1024 nt
	global_store_dwordx2 v3, v[78:79], s[6:7] offset:1536 nt
	s_add_u32 s6, s6, 0x400000
	s_addc_u32 s7, s7, 0
	global_load_dwordx4 v[40:43], v2, s[4:5]
	global_load_dwordx4 v[44:47], v2, s[4:5] offset:1024
	global_load_dwordx4 v[48:51], v2, s[4:5] offset:2048
	global_load_dwordx4 v[52:55], v2, s[4:5] offset:3072
	s_add_u32 s4, s4, 0x800000
	s_addc_u32 s5, s5, 0
	s_waitcnt vmcnt(8)
	v_pk_fma_f32 v[56:57], v[56:57], v[24:25], v[8:9]
	v_pk_fma_f32 v[58:59], v[58:59], v[26:27], v[10:11]
	v_pk_fma_f32 v[60:61], v[60:61], v[28:29], v[12:13]
	v_pk_fma_f32 v[62:63], v[62:63], v[30:31], v[14:15]
	v_pk_fma_f32 v[64:65], v[64:65], v[32:33], v[16:17]
	v_pk_fma_f32 v[66:67], v[66:67], v[34:35], v[18:19]
	v_pk_fma_f32 v[68:69], v[68:69], v[36:37], v[20:21]
	v_pk_fma_f32 v[70:71], v[70:71], v[38:39], v[22:23]
	v_cvt_pk_bf16_f32 v80, v56, v57
	v_cvt_pk_bf16_f32 v81, v58, v59
	v_cvt_pk_bf16_f32 v82, v60, v61
	v_cvt_pk_bf16_f32 v83, v62, v63
	v_cvt_pk_bf16_f32 v84, v64, v65
	v_cvt_pk_bf16_f32 v85, v66, v67
	v_cvt_pk_bf16_f32 v86, v68, v69
	v_cvt_pk_bf16_f32 v87, v70, v71
	global_store_dwordx2 v3, v[80:81], s[6:7] nt
	global_store_dwordx2 v3, v[82:83], s[6:7] offset:512 nt
	global_store_dwordx2 v3, v[84:85], s[6:7] offset:1024 nt
	global_store_dwordx2 v3, v[86:87], s[6:7] offset:1536 nt
	s_add_u32 s6, s6, 0x400000
	s_addc_u32 s7, s7, 0
	global_load_dwordx4 v[56:59], v2, s[4:5]
	global_load_dwordx4 v[60:63], v2, s[4:5] offset:1024
	global_load_dwordx4 v[64:67], v2, s[4:5] offset:2048
	global_load_dwordx4 v[68:71], v2, s[4:5] offset:3072
	s_add_u32 s4, s4, 0x800000
	s_addc_u32 s5, s5, 0
	s_waitcnt vmcnt(8)
	v_pk_fma_f32 v[40:41], v[40:41], v[24:25], v[8:9]
	v_pk_fma_f32 v[42:43], v[42:43], v[26:27], v[10:11]
	v_pk_fma_f32 v[44:45], v[44:45], v[28:29], v[12:13]
	v_pk_fma_f32 v[46:47], v[46:47], v[30:31], v[14:15]
	v_pk_fma_f32 v[48:49], v[48:49], v[32:33], v[16:17]
	v_pk_fma_f32 v[50:51], v[50:51], v[34:35], v[18:19]
	v_pk_fma_f32 v[52:53], v[52:53], v[36:37], v[20:21]
	v_pk_fma_f32 v[54:55], v[54:55], v[38:39], v[22:23]
	v_cvt_pk_bf16_f32 v72, v40, v41
	v_cvt_pk_bf16_f32 v73, v42, v43
	v_cvt_pk_bf16_f32 v74, v44, v45
	v_cvt_pk_bf16_f32 v75, v46, v47
	v_cvt_pk_bf16_f32 v76, v48, v49
	v_cvt_pk_bf16_f32 v77, v50, v51
	v_cvt_pk_bf16_f32 v78, v52, v53
	v_cvt_pk_bf16_f32 v79, v54, v55
	global_store_dwordx2 v3, v[72:73], s[6:7] nt
	global_store_dwordx2 v3, v[74:75], s[6:7] offset:512 nt
	global_store_dwordx2 v3, v[76:77], s[6:7] offset:1024 nt
	global_store_dwordx2 v3, v[78:79], s[6:7] offset:1536 nt
	s_add_u32 s6, s6, 0x400000
	s_addc_u32 s7, s7, 0
	s_waitcnt vmcnt(4)
	v_pk_fma_f32 v[56:57], v[56:57], v[24:25], v[8:9]
	v_pk_fma_f32 v[58:59], v[58:59], v[26:27], v[10:11]
	v_pk_fma_f32 v[60:61], v[60:61], v[28:29], v[12:13]
	v_pk_fma_f32 v[62:63], v[62:63], v[30:31], v[14:15]
	v_pk_fma_f32 v[64:65], v[64:65], v[32:33], v[16:17]
	v_pk_fma_f32 v[66:67], v[66:67], v[34:35], v[18:19]
	v_pk_fma_f32 v[68:69], v[68:69], v[36:37], v[20:21]
	v_pk_fma_f32 v[70:71], v[70:71], v[38:39], v[22:23]
	v_cvt_pk_bf16_f32 v80, v56, v57
	v_cvt_pk_bf16_f32 v81, v58, v59
	v_cvt_pk_bf16_f32 v82, v60, v61
	v_cvt_pk_bf16_f32 v83, v62, v63
	v_cvt_pk_bf16_f32 v84, v64, v65
	v_cvt_pk_bf16_f32 v85, v66, v67
	v_cvt_pk_bf16_f32 v86, v68, v69
	v_cvt_pk_bf16_f32 v87, v70, v71
	global_store_dwordx2 v3, v[80:81], s[6:7] nt
	global_store_dwordx2 v3, v[82:83], s[6:7] offset:512 nt
	global_store_dwordx2 v3, v[84:85], s[6:7] offset:1024 nt
	global_store_dwordx2 v3, v[86:87], s[6:7] offset:1536 nt
	s_add_u32 s6, s6, 0x400000
	s_addc_u32 s7, s7, 0
	s_cmp_lt_u32 s33, 32
	s_cbranch_scc0 .Lp1_done
	s_add_u32 s4, s56, s10
	s_addc_u32 s5, s57, 0
	s_add_u32 s6, s54, s11
	s_addc_u32 s7, s55, 0
	s_add_u32 s6, s6, 0x2000000
	s_addc_u32 s7, s7, 0
	global_load_dwordx4 v[40:43], v2, s[4:5]
	global_load_dwordx4 v[44:47], v2, s[4:5] offset:1024
	global_load_dwordx4 v[48:51], v2, s[4:5] offset:2048
	global_load_dwordx4 v[52:55], v2, s[4:5] offset:3072
	ds_read_b128 v[8:11], v2 offset:8192
	ds_read_b128 v[12:15], v2 offset:9216
	ds_read_b128 v[16:19], v2 offset:10240
	ds_read_b128 v[20:23], v2 offset:11264
	ds_read_b128 v[24:27], v2 offset:12288
	ds_read_b128 v[28:31], v2 offset:13312
	ds_read_b128 v[32:35], v2 offset:14336
	ds_read_b128 v[36:39], v2 offset:15360
	s_waitcnt lgkmcnt(0)
	v_pk_add_f32 v[24:25], v[24:25], 1.0 op_sel_hi:[1,0]
	v_pk_add_f32 v[26:27], v[26:27], 1.0 op_sel_hi:[1,0]
	v_pk_add_f32 v[28:29], v[28:29], 1.0 op_sel_hi:[1,0]
	v_pk_add_f32 v[30:31], v[30:31], 1.0 op_sel_hi:[1,0]
	v_pk_add_f32 v[32:33], v[32:33], 1.0 op_sel_hi:[1,0]
	v_pk_add_f32 v[34:35], v[34:35], 1.0 op_sel_hi:[1,0]
	v_pk_add_f32 v[36:37], v[36:37], 1.0 op_sel_hi:[1,0]
	v_pk_add_f32 v[38:39], v[38:39], 1.0 op_sel_hi:[1,0]
	s_waitcnt vmcnt(0)
	v_pk_fma_f32 v[40:41], v[40:41], v[24:25], v[8:9]
	v_pk_fma_f32 v[42:43], v[42:43], v[26:27], v[10:11]
	v_pk_fma_f32 v[44:45], v[44:45], v[28:29], v[12:13]
	v_pk_fma_f32 v[46:47], v[46:47], v[30:31], v[14:15]
	v_pk_fma_f32 v[48:49], v[48:49], v[32:33], v[16:17]
	v_pk_fma_f32 v[50:51], v[50:51], v[34:35], v[18:19]
	v_pk_fma_f32 v[52:53], v[52:53], v[36:37], v[20:21]
	v_pk_fma_f32 v[54:55], v[54:55], v[38:39], v[22:23]
	v_cvt_pk_bf16_f32 v72, v40, v41
	v_cvt_pk_bf16_f32 v73, v42, v43
	v_cvt_pk_bf16_f32 v74, v44, v45
	v_cvt_pk_bf16_f32 v75, v46, v47
	v_cvt_pk_bf16_f32 v76, v48, v49
	v_cvt_pk_bf16_f32 v77, v50, v51
	v_cvt_pk_bf16_f32 v78, v52, v53
	v_cvt_pk_bf16_f32 v79, v54, v55
	global_store_dwordx2 v3, v[72:73], s[6:7] nt
	global_store_dwordx2 v3, v[74:75], s[6:7] offset:512 nt
	global_store_dwordx2 v3, v[76:77], s[6:7] offset:1024 nt
	global_store_dwordx2 v3, v[78:79], s[6:7] offset:1536 nt

.LBB0_839:
	s_or_b64 exec, exec, s[2:3]
	global_load_dword v3, v[46:47], off offset:32
	global_load_dword v33, v[48:49], off offset:32
	global_load_dwordx4 v[56:59], v[26:27], off
	global_load_dwordx4 v[60:63], v[28:29], off
	global_load_dwordx4 v[70:73], v[22:23], off
	global_load_dwordx4 v[74:77], v[24:25], off
	v_mov_b32_e32 v35, v5
	v_lshl_add_u64 v[46:47], v[50:51], 0, v[34:35]
	global_load_dwordx2 v[48:49], v[46:47], off
	s_waitcnt vmcnt(9)
	v_lshlrev_b32_e32 v50, 16, v44
	v_lshlrev_b32_e32 v51, 16, v45
	s_waitcnt vmcnt(8)
	v_lshlrev_b32_e32 v64, 16, v42
	v_lshlrev_b32_e32 v65, 16, v43
	v_and_b32_e32 v45, 0xffff0000, v45
	v_and_b32_e32 v44, 0xffff0000, v44
	v_and_b32_e32 v43, 0xffff0000, v43
	v_and_b32_e32 v42, 0xffff0000, v42
	v_pk_add_f32 v[50:51], v[50:51], v[64:65]
	v_pk_add_f32 v[42:43], v[44:45], v[42:43]
	s_waitcnt vmcnt(7)
	v_lshlrev_b32_e32 v78, 16, v40
	v_pk_add_f32 v[64:65], v[50:51], v[42:43]
	v_lshlrev_b32_e32 v79, 16, v41
	v_add_f32_e32 v35, v64, v65
	v_lshlrev_b32_e32 v83, 16, v55
	v_lshlrev_b32_e32 v82, 16, v54
	v_add_f32_dpp v35, v35, v35 quad_perm:[1,0,3,2] row_mask:0xf bank_mask:0xf bound_ctrl:1
	v_pk_add_f32 v[44:45], v[82:83], v[78:79] neg_lo:[0,1] neg_hi:[0,1]
	v_lshlrev_b32_e32 v81, 16, v53
	v_add_f32_dpp v35, v35, v35 quad_perm:[2,3,0,1] row_mask:0xf bank_mask:0xf bound_ctrl:1
	v_lshlrev_b32_e32 v80, 16, v52
	v_and_b32_e32 v40, 0xffff0000, v40
	v_add_f32_dpp v35, v35, v35 row_ror:4 row_mask:0xf bank_mask:0xf bound_ctrl:1
	v_and_b32_e32 v41, 0xffff0000, v41
	v_and_b32_e32 v55, 0xffff0000, v55
	v_add_f32_dpp v35, v35, v35 row_ror:8 row_mask:0xf bank_mask:0xf bound_ctrl:1
	v_mul_f32_e32 v64, 0x3c800000, v35
	v_pk_add_f32 v[50:51], v[50:51], v[64:65] op_sel_hi:[1,0] neg_lo:[0,1] neg_hi:[0,1]
	v_pk_add_f32 v[42:43], v[42:43], v[64:65] op_sel_hi:[1,0] neg_lo:[0,1] neg_hi:[0,1]
	v_mov_b32_e32 v64, v50
	v_mov_b32_e32 v65, v42
	v_mov_b32_e32 v82, v43
	v_mov_b32_e32 v83, v51
	v_pk_mul_f32 v[64:65], v[64:65], v[64:65]
	v_pk_mul_f32 v[82:83], v[82:83], v[82:83]
	v_add_f32_e32 v35, v64, v65
	v_add_f32_e32 v35, v83, v35
	v_add_f32_e32 v35, v82, v35
	v_and_b32_e32 v54, 0xffff0000, v54
	v_and_b32_e32 v53, 0xffff0000, v53
	v_add_f32_dpp v35, v35, v35 quad_perm:[1,0,3,2] row_mask:0xf bank_mask:0xf bound_ctrl:1
	v_and_b32_e32 v52, 0xffff0000, v52
	v_pk_add_f32 v[54:55], v[54:55], v[40:41] neg_lo:[0,1] neg_hi:[0,1]
	v_add_f32_dpp v35, v35, v35 quad_perm:[2,3,0,1] row_mask:0xf bank_mask:0xf bound_ctrl:1
	v_pk_add_f32 v[52:53], v[52:53], v[40:41] neg_lo:[0,1] neg_hi:[0,1]
	v_add_u32_e32 v2, s14, v2
	v_add_f32_dpp v35, v35, v35 row_ror:4 row_mask:0xf bank_mask:0xf bound_ctrl:1
	s_waitcnt vmcnt(5)
	v_add_f32_e32 v82, v3, v33
	v_add_f32_dpp v35, v35, v35 row_ror:8 row_mask:0xf bank_mask:0xf bound_ctrl:1
	v_fmamk_f32 v35, v35, 0x3c800000, v66
	v_mul_f32_e32 v64, 0x4b800000, v35
	v_cmp_gt_f32_e32 vcc, s18, v35
	s_waitcnt vmcnt(4)
	v_mov_b32_e32 v85, v58
	v_mov_b32_e32 v58, v57
	v_cndmask_b32_e32 v35, v35, v64, vcc
	v_rsq_f32_e32 v35, v35
	v_pk_add_f32 v[64:65], v[80:81], v[78:79] neg_lo:[0,1] neg_hi:[0,1]
	v_mov_b32_e32 v84, v56
	s_waitcnt vmcnt(3)
	v_mov_b32_e32 v87, v62
	v_mul_f32_e32 v80, 0x45800000, v35
	v_cndmask_b32_e32 v80, v35, v80, vcc
	s_waitcnt vmcnt(2)
	v_mov_b32_e32 v89, v72
	s_waitcnt vmcnt(1)
	v_mov_b32_e32 v91, v76
	v_pk_fma_f32 v[40:41], v[54:55], v[58:59], v[40:41]
	v_mov_b32_e32 v62, v61
	v_pk_mul_f32 v[42:43], v[42:43], v[80:81] op_sel_hi:[1,0]
	v_mov_b32_e32 v72, v71
	v_mov_b32_e32 v76, v75
	v_pk_mul_f32 v[50:51], v[50:51], v[80:81] op_sel_hi:[1,0]
	v_mov_b32_e32 v86, v60
	v_mov_b32_e32 v88, v70
	v_mov_b32_e32 v90, v74
	v_pk_fma_f32 v[44:45], v[44:45], v[84:85], v[78:79]
	v_pk_fma_f32 v[40:41], v[52:53], v[62:63], v[40:41]
	v_pk_fma_f32 v[42:43], v[72:73], v[42:43], v[76:77]
	v_pk_fma_f32 v[50:51], v[88:89], v[50:51], v[90:91]
	s_waitcnt vmcnt(0)
	v_lshlrev_b32_e32 v55, 16, v49
	v_lshlrev_b32_e32 v54, 16, v48
	v_and_b32_e32 v49, 0xffff0000, v49
	v_and_b32_e32 v48, 0xffff0000, v48
	v_pk_fma_f32 v[44:45], v[64:65], v[86:87], v[44:45]
	v_pk_fma_f32 v[40:41], v[82:83], v[40:41], v[42:43] op_sel_hi:[0,1,1]
	v_pk_fma_f32 v[44:45], v[82:83], v[44:45], v[50:51] op_sel_hi:[0,1,1]
	v_pk_mul_f32 v[40:41], v[40:41], v[48:49]
	v_pk_mul_f32 v[44:45], v[44:45], v[54:55]
	v_and_b32_sdwa v35, v41, v69 dst_sel:DWORD dst_unused:UNUSED_PAD src0_sel:WORD_1 src1_sel:DWORD
	v_and_b32_sdwa v42, v40, v69 dst_sel:DWORD dst_unused:UNUSED_PAD src0_sel:WORD_1 src1_sel:DWORD
	v_and_b32_sdwa v3, v45, v69 dst_sel:DWORD dst_unused:UNUSED_PAD src0_sel:WORD_1 src1_sel:DWORD
	v_and_b32_sdwa v33, v44, v69 dst_sel:DWORD dst_unused:UNUSED_PAD src0_sel:WORD_1 src1_sel:DWORD
	v_add3_u32 v35, v41, v35, s19
	v_add3_u32 v40, v40, v42, s19
	v_add3_u32 v33, v44, v33, s19
	v_add3_u32 v3, v45, v3, s19
	v_and_b32_e32 v35, 0xffff0000, v35
	v_and_b32_e32 v40, 0xffff0000, v40
	v_cmp_lt_i32_e32 vcc, s20, v2
	v_or_b32_sdwa v41, v35, v3 dst_sel:DWORD dst_unused:UNUSED_PAD src0_sel:DWORD src1_sel:WORD_1
	v_or_b32_sdwa v40, v40, v33 dst_sel:DWORD dst_unused:UNUSED_PAD src0_sel:DWORD src1_sel:WORD_1
	s_or_b64 s[8:9], vcc, s[8:9]
	global_store_dwordx2 v[46:47], v[40:41], off nt
	s_andn2_b64 exec, exec, s[8:9]
	s_cbranch_execz .LBB0_852

.LBB0_844:
	s_or_b64 exec, exec, s[12:13]
	v_mad_i64_i32 v[48:49], s[12:13], v3, 48, v[30:31]
	v_ashrrev_i32_e32 v3, 31, v2
	global_load_dwordx4 v[70:73], v[6:7], off
	global_load_dwordx4 v[74:77], v[10:11], off
	global_load_dwordx4 v[78:81], v[8:9], off
	global_load_dwordx4 v[82:85], v[12:13], off
	v_lshlrev_b64 v[50:51], 11, v[2:3]
	v_mad_i64_i32 v[46:47], s[12:13], v2, 48, v[30:31]
	v_lshl_add_u64 v[50:51], s[54:55], 0, v[50:51]
	global_load_dword v33, v[46:47], off
	global_load_dword v35, v[48:49], off
	v_lshl_add_u64 v[64:65], v[50:51], 0, v[4:5]
	global_load_dwordx2 v[86:87], v[64:65], off
	s_waitcnt vmcnt(0)
	v_lshlrev_b32_e32 v88, 16, v60
	v_lshlrev_b32_e32 v89, 16, v61
	v_lshlrev_b32_e32 v90, 16, v58
	v_lshlrev_b32_e32 v91, 16, v59
	v_and_b32_e32 v61, 0xffff0000, v61
	v_and_b32_e32 v60, 0xffff0000, v60
	v_and_b32_e32 v59, 0xffff0000, v59
	v_and_b32_e32 v58, 0xffff0000, v58
	v_pk_add_f32 v[88:89], v[88:89], v[90:91]
	v_pk_add_f32 v[58:59], v[60:61], v[58:59]
	v_lshlrev_b32_e32 v92, 16, v56
	v_pk_add_f32 v[60:61], v[88:89], v[58:59]
	v_and_b32_e32 v56, 0xffff0000, v56
	v_add_f32_e32 v3, v60, v61
	v_lshlrev_b32_e32 v93, 16, v57
	v_and_b32_e32 v57, 0xffff0000, v57
	v_add_f32_dpp v3, v3, v3 quad_perm:[1,0,3,2] row_mask:0xf bank_mask:0xf bound_ctrl:1
	v_lshlrev_b32_e32 v97, 16, v55
	v_lshlrev_b32_e32 v96, 16, v54
	v_add_f32_dpp v3, v3, v3 quad_perm:[2,3,0,1] row_mask:0xf bank_mask:0xf bound_ctrl:1
	v_and_b32_e32 v55, 0xffff0000, v55
	v_and_b32_e32 v54, 0xffff0000, v54
	v_add_f32_dpp v3, v3, v3 row_ror:4 row_mask:0xf bank_mask:0xf bound_ctrl:1
	v_lshlrev_b32_e32 v95, 16, v63
	v_lshlrev_b32_e32 v94, 16, v62
	v_add_f32_dpp v3, v3, v3 row_ror:8 row_mask:0xf bank_mask:0xf bound_ctrl:1
	v_mul_f32_e32 v60, 0x3c800000, v3
	v_pk_add_f32 v[88:89], v[88:89], v[60:61] op_sel_hi:[1,0] neg_lo:[0,1] neg_hi:[0,1]
	v_pk_add_f32 v[58:59], v[58:59], v[60:61] op_sel_hi:[1,0] neg_lo:[0,1] neg_hi:[0,1]
	v_mov_b32_e32 v60, v88
	v_mov_b32_e32 v61, v58
	v_mov_b32_e32 v90, v59
	v_mov_b32_e32 v91, v89
	v_pk_mul_f32 v[60:61], v[60:61], v[60:61]
	v_pk_mul_f32 v[90:91], v[90:91], v[90:91]
	v_add_f32_e32 v3, v60, v61
	v_add_f32_e32 v3, v91, v3
	v_add_f32_e32 v3, v90, v3
	v_and_b32_e32 v63, 0xffff0000, v63
	v_and_b32_e32 v62, 0xffff0000, v62
	v_add_f32_dpp v3, v3, v3 quad_perm:[1,0,3,2] row_mask:0xf bank_mask:0xf bound_ctrl:1
	v_pk_add_f32 v[60:61], v[96:97], v[92:93] neg_lo:[0,1] neg_hi:[0,1]
	v_pk_add_f32 v[54:55], v[54:55], v[56:57] neg_lo:[0,1] neg_hi:[0,1]
	v_add_f32_dpp v3, v3, v3 quad_perm:[2,3,0,1] row_mask:0xf bank_mask:0xf bound_ctrl:1
	v_pk_add_f32 v[90:91], v[94:95], v[92:93] neg_lo:[0,1] neg_hi:[0,1]
	v_mov_b32_e32 v100, v70
	v_add_f32_dpp v3, v3, v3 row_ror:4 row_mask:0xf bank_mask:0xf bound_ctrl:1
	v_mov_b32_e32 v97, v76
	v_mov_b32_e32 v76, v75
	v_add_f32_dpp v3, v3, v3 row_ror:8 row_mask:0xf bank_mask:0xf bound_ctrl:1
	v_fmamk_f32 v3, v3, 0x3c800000, v66
	v_mul_f32_e32 v53, 0x4b800000, v3
	v_cmp_gt_f32_e32 vcc, s18, v3
	v_mov_b32_e32 v96, v74
	v_mov_b32_e32 v99, v84
	v_cndmask_b32_e32 v3, v3, v53, vcc
	v_rsq_f32_e32 v3, v3
	v_pk_fma_f32 v[54:55], v[54:55], v[76:77], v[56:57]
	v_pk_add_f32 v[56:57], v[62:63], v[56:57] neg_lo:[0,1] neg_hi:[0,1]
	v_mov_b32_e32 v84, v83
	v_mul_f32_e32 v53, 0x45800000, v3
	v_cndmask_b32_e32 v94, v3, v53, vcc
	v_pk_mul_f32 v[88:89], v[88:89], v[94:95] op_sel_hi:[1,0]
	v_mov_b32_e32 v98, v82
	v_mov_b32_e32 v101, v72
	v_mov_b32_e32 v102, v78
	v_mov_b32_e32 v103, v80
	v_pk_fma_f32 v[60:61], v[60:61], v[96:97], v[92:93]
	v_pk_fma_f32 v[54:55], v[56:57], v[84:85], v[54:55]
	v_pk_mul_f32 v[56:57], v[58:59], v[94:95] op_sel_hi:[1,0]
	v_mov_b32_e32 v72, v71
	v_mov_b32_e32 v80, v79
	v_add_f32_e32 v70, v33, v35
	v_pk_fma_f32 v[88:89], v[100:101], v[88:89], v[102:103]
	v_pk_fma_f32 v[60:61], v[90:91], v[98:99], v[60:61]
	v_pk_fma_f32 v[56:57], v[72:73], v[56:57], v[80:81]
	v_pk_fma_f32 v[60:61], v[70:71], v[60:61], v[88:89] op_sel_hi:[0,1,1]
	v_lshlrev_b32_e32 v89, 16, v87
	v_lshlrev_b32_e32 v88, 16, v86
	v_and_b32_e32 v87, 0xffff0000, v87
	v_and_b32_e32 v86, 0xffff0000, v86
	v_pk_fma_f32 v[54:55], v[70:71], v[54:55], v[56:57] op_sel_hi:[0,1,1]
	v_pk_mul_f32 v[54:55], v[54:55], v[86:87]
	v_pk_mul_f32 v[60:61], v[60:61], v[88:89]
	v_and_b32_sdwa v35, v55, v69 dst_sel:DWORD dst_unused:UNUSED_PAD src0_sel:WORD_1 src1_sel:DWORD
	v_and_b32_sdwa v53, v54, v69 dst_sel:DWORD dst_unused:UNUSED_PAD src0_sel:WORD_1 src1_sel:DWORD
	v_and_b32_sdwa v3, v61, v69 dst_sel:DWORD dst_unused:UNUSED_PAD src0_sel:WORD_1 src1_sel:DWORD
	v_and_b32_sdwa v33, v60, v69 dst_sel:DWORD dst_unused:UNUSED_PAD src0_sel:WORD_1 src1_sel:DWORD
	v_add3_u32 v35, v55, v35, s19
	v_add3_u32 v53, v54, v53, s19
	v_add3_u32 v33, v60, v33, s19
	v_add3_u32 v3, v61, v3, s19
	v_and_b32_e32 v35, 0xffff0000, v35
	v_and_b32_e32 v53, 0xffff0000, v53
	v_or_b32_sdwa v55, v35, v3 dst_sel:DWORD dst_unused:UNUSED_PAD src0_sel:DWORD src1_sel:WORD_1
	v_or_b32_sdwa v54, v53, v33 dst_sel:DWORD dst_unused:UNUSED_PAD src0_sel:DWORD src1_sel:WORD_1
	v_mov_b32_e32 v33, v5
	global_store_dwordx2 v[64:65], v[54:55], off nt
	v_lshl_add_u64 v[54:55], v[42:43], 0, v[32:33]
	v_lshl_add_u64 v[56:57], v[44:45], 0, v[32:33]
	v_lshl_add_u64 v[64:65], v[40:41], 0, v[32:33]
	global_load_dwordx2 v[60:61], v[54:55], off
	global_load_dwordx2 v[58:59], v[56:57], off
	s_nop 0
	global_load_dwordx2 v[56:57], v[64:65], off offset:3072
	v_mov_b32_e32 v53, 0
	s_and_saveexec_b64 s[12:13], s[2:3]
	s_cbranch_execz .LBB0_846
	global_load_dwordx2 v[52:53], v[64:65], off offset:-3072

.LBB0_848:
	s_or_b64 exec, exec, s[12:13]
	global_load_dword v3, v[46:47], off offset:16
	global_load_dword v35, v[48:49], off offset:16
	global_load_dwordx4 v[70:73], v[18:19], off
	global_load_dwordx4 v[74:77], v[20:21], off
	global_load_dwordx4 v[78:81], v[14:15], off
	global_load_dwordx4 v[82:85], v[16:17], off
	v_mov_b32_e32 v33, v5
	v_lshl_add_u64 v[64:65], v[50:51], 0, v[32:33]
	global_load_dwordx2 v[86:87], v[64:65], off
	s_waitcnt vmcnt(9)
	v_lshlrev_b32_e32 v88, 16, v60
	v_lshlrev_b32_e32 v89, 16, v61
	s_waitcnt vmcnt(8)
	v_lshlrev_b32_e32 v90, 16, v58
	v_lshlrev_b32_e32 v91, 16, v59
	v_and_b32_e32 v61, 0xffff0000, v61
	v_and_b32_e32 v60, 0xffff0000, v60
	v_and_b32_e32 v59, 0xffff0000, v59
	v_and_b32_e32 v58, 0xffff0000, v58
	v_pk_add_f32 v[88:89], v[88:89], v[90:91]
	v_pk_add_f32 v[58:59], v[60:61], v[58:59]
	s_waitcnt vmcnt(7)
	v_lshlrev_b32_e32 v92, 16, v56
	v_pk_add_f32 v[90:91], v[88:89], v[58:59]
	v_lshlrev_b32_e32 v93, 16, v57
	v_add_f32_e32 v33, v90, v91
	v_lshlrev_b32_e32 v97, 16, v53
	v_lshlrev_b32_e32 v96, 16, v52
	v_add_f32_dpp v33, v33, v33 quad_perm:[1,0,3,2] row_mask:0xf bank_mask:0xf bound_ctrl:1
	v_pk_add_f32 v[60:61], v[96:97], v[92:93] neg_lo:[0,1] neg_hi:[0,1]
	v_and_b32_e32 v56, 0xffff0000, v56
	v_add_f32_dpp v33, v33, v33 quad_perm:[2,3,0,1] row_mask:0xf bank_mask:0xf bound_ctrl:1
	v_and_b32_e32 v57, 0xffff0000, v57
	v_lshlrev_b32_e32 v95, 16, v63
	v_add_f32_dpp v33, v33, v33 row_ror:4 row_mask:0xf bank_mask:0xf bound_ctrl:1
	v_lshlrev_b32_e32 v94, 16, v62
	v_and_b32_e32 v53, 0xffff0000, v53
	v_add_f32_dpp v33, v33, v33 row_ror:8 row_mask:0xf bank_mask:0xf bound_ctrl:1
	v_mul_f32_e32 v90, 0x3c800000, v33
	v_pk_add_f32 v[88:89], v[88:89], v[90:91] op_sel_hi:[1,0] neg_lo:[0,1] neg_hi:[0,1]
	v_pk_add_f32 v[58:59], v[58:59], v[90:91] op_sel_hi:[1,0] neg_lo:[0,1] neg_hi:[0,1]
	v_mov_b32_e32 v90, v88
	v_mov_b32_e32 v91, v58
	v_mov_b32_e32 v96, v59
	v_mov_b32_e32 v97, v89
	v_pk_mul_f32 v[90:91], v[90:91], v[90:91]
	v_pk_mul_f32 v[96:97], v[96:97], v[96:97]
	v_add_f32_e32 v33, v90, v91
	v_add_f32_e32 v33, v97, v33
	v_add_f32_e32 v33, v96, v33
	v_and_b32_e32 v52, 0xffff0000, v52
	v_and_b32_e32 v63, 0xffff0000, v63
	v_add_f32_dpp v33, v33, v33 quad_perm:[1,0,3,2] row_mask:0xf bank_mask:0xf bound_ctrl:1
	v_and_b32_e32 v62, 0xffff0000, v62
	v_pk_add_f32 v[90:91], v[94:95], v[92:93] neg_lo:[0,1] neg_hi:[0,1]
	v_add_f32_dpp v33, v33, v33 quad_perm:[2,3,0,1] row_mask:0xf bank_mask:0xf bound_ctrl:1
	v_pk_add_f32 v[52:53], v[52:53], v[56:57] neg_lo:[0,1] neg_hi:[0,1]
	v_pk_add_f32 v[62:63], v[62:63], v[56:57] neg_lo:[0,1] neg_hi:[0,1]
	v_add_f32_dpp v33, v33, v33 row_ror:4 row_mask:0xf bank_mask:0xf bound_ctrl:1
	s_waitcnt vmcnt(5)
	v_add_f32_e32 v96, v3, v35
	v_add_f32_dpp v33, v33, v33 row_ror:8 row_mask:0xf bank_mask:0xf bound_ctrl:1
	v_fmamk_f32 v33, v33, 0x3c800000, v66
	v_mul_f32_e32 v55, 0x4b800000, v33
	v_cmp_gt_f32_e32 vcc, s18, v33
	s_waitcnt vmcnt(4)
	v_mov_b32_e32 v99, v72
	v_mov_b32_e32 v72, v71
	v_cndmask_b32_e32 v33, v33, v55, vcc
	v_rsq_f32_e32 v33, v33
	v_mov_b32_e32 v98, v70
	s_waitcnt vmcnt(3)
	v_mov_b32_e32 v101, v76
	s_waitcnt vmcnt(2)
	v_mov_b32_e32 v103, v80
	v_mul_f32_e32 v55, 0x45800000, v33
	v_cndmask_b32_e32 v94, v33, v55, vcc
	s_waitcnt vmcnt(1)
	v_mov_b32_e32 v105, v84
	v_pk_fma_f32 v[52:53], v[52:53], v[72:73], v[56:57]
	v_mov_b32_e32 v76, v75
	v_pk_mul_f32 v[58:59], v[58:59], v[94:95] op_sel_hi:[1,0]
	v_mov_b32_e32 v80, v79
	v_mov_b32_e32 v84, v83
	v_pk_mul_f32 v[88:89], v[88:89], v[94:95] op_sel_hi:[1,0]
	v_mov_b32_e32 v100, v74
	v_mov_b32_e32 v102, v78
	v_mov_b32_e32 v104, v82
	v_pk_fma_f32 v[60:61], v[60:61], v[98:99], v[92:93]
	v_pk_fma_f32 v[52:53], v[62:63], v[76:77], v[52:53]
	v_pk_fma_f32 v[58:59], v[80:81], v[58:59], v[84:85]
	v_pk_fma_f32 v[70:71], v[102:103], v[88:89], v[104:105]
	s_waitcnt vmcnt(0)
	v_and_b32_e32 v73, 0xffff0000, v87
	v_and_b32_e32 v72, 0xffff0000, v86
	v_pk_fma_f32 v[60:61], v[90:91], v[100:101], v[60:61]
	v_pk_fma_f32 v[52:53], v[96:97], v[52:53], v[58:59] op_sel_hi:[0,1,1]
	v_lshlrev_b32_e32 v57, 16, v87
	v_lshlrev_b32_e32 v56, 16, v86
	v_pk_fma_f32 v[60:61], v[96:97], v[60:61], v[70:71] op_sel_hi:[0,1,1]
	v_pk_mul_f32 v[52:53], v[52:53], v[72:73]
	v_pk_mul_f32 v[56:57], v[60:61], v[56:57]
	v_and_b32_sdwa v35, v53, v69 dst_sel:DWORD dst_unused:UNUSED_PAD src0_sel:WORD_1 src1_sel:DWORD
	v_and_b32_sdwa v55, v52, v69 dst_sel:DWORD dst_unused:UNUSED_PAD src0_sel:WORD_1 src1_sel:DWORD
	v_and_b32_sdwa v3, v57, v69 dst_sel:DWORD dst_unused:UNUSED_PAD src0_sel:WORD_1 src1_sel:DWORD
	v_and_b32_sdwa v33, v56, v69 dst_sel:DWORD dst_unused:UNUSED_PAD src0_sel:WORD_1 src1_sel:DWORD
	v_add3_u32 v35, v53, v35, s19
	v_add3_u32 v52, v52, v55, s19
	v_add3_u32 v33, v56, v33, s19
	v_add3_u32 v3, v57, v3, s19
	v_and_b32_e32 v35, 0xffff0000, v35
	v_and_b32_e32 v52, 0xffff0000, v52
	v_or_b32_sdwa v53, v35, v3 dst_sel:DWORD dst_unused:UNUSED_PAD src0_sel:DWORD src1_sel:WORD_1
	v_or_b32_sdwa v52, v52, v33 dst_sel:DWORD dst_unused:UNUSED_PAD src0_sel:DWORD src1_sel:WORD_1
	v_mov_b32_e32 v35, v5
	global_store_dwordx2 v[64:65], v[52:53], off nt
	v_lshl_add_u64 v[42:43], v[42:43], 0, v[34:35]
	v_lshl_add_u64 v[52:53], v[44:45], 0, v[34:35]
	v_lshl_add_u64 v[56:57], v[40:41], 0, v[34:35]
	global_load_dwordx2 v[44:45], v[42:43], off
	s_nop 0
	global_load_dwordx2 v[42:43], v[52:53], off
	global_load_dwordx2 v[40:41], v[56:57], off offset:3072
	v_mov_b32_e32 v55, 0
	s_and_saveexec_b64 s[12:13], s[2:3]
	s_cbranch_execz .LBB0_850
	global_load_dwordx2 v[54:55], v[56:57], off offset:-3072
